# diff-attn loop: s_setprio 1 around the QK and PV MFMA sections (0 elsewhere), on top of the scalar-tmax/wait cleanup
# speedup vs baseline: 1.0019x; 1.0019x over previous
; #define MFMA32(a, b, c) __builtin_amdgcn_mfma_f32_32x32x16_bf16((a), (b), (c), 0, 0, 0)
; DI void diff_unit(unsigned char* smem, const bf16* __restrict__ QKV, bf16* __restrict__ Y, int h, int qb, float lam, float outscale, const float* __restrict__ gain, float kn0, float kn1, int tid) {
;     ...
;                 bf16x8 kf[8];
; #pragma unroll
;                 for (int kh = 0; kh < 2; ++kh)
; #pragma unroll
;                     for (int ds = 0; ds < 4; ++ds) kf[kh * 4 + ds] = *(const bf16x8*)(tb + koff[ds] + kh * 8192);
;                 if (j < qb) {
; #pragma unroll
;                     for (int kh = 0; kh < 2; ++kh) { int cio = D3_CI + kh * 64; asm volatile("" : "+v"(cio)); p[kh] = *(const f32x16*)(smem + cio); }
;                 } else {
; #pragma unroll
;                     for (int kh = 0; kh < 2; ++kh)
; #pragma unroll
;                         for (int r = 0; r < 16; ++r) p[kh][r] = 0.f;
;                 }
;                 __builtin_amdgcn_sched_barrier(0);
; #pragma unroll
;                 for (int ds = 0; ds < 4; ++ds)
; #pragma unroll
;                     for (int kh = 0; kh < 2; ++kh) p[kh] = MFMA32(kf[kh * 4 + ds], qf[ds], p[kh]);
;                 __builtin_amdgcn_sched_barrier(0);
.Lmy_ci_fast:
	v_add_u32_e32 v159, v191, v190
	v_add_u32_e32 v161, 0xffffffbf, v159
	s_waitcnt lgkmcnt(6)
	s_setprio 1
	v_mfma_f32_32x32x16_bf16 v[80:95], v[140:143], v[112:115], v[220:235]
	v_mfma_f32_32x32x16_bf16 v[96:111], v[144:147], v[112:115], v[236:251]
.Lmy_ci_join:
	s_waitcnt lgkmcnt(4)
	v_mfma_f32_32x32x16_bf16 v[80:95], v[136:139], v[116:119], v[80:95]
	v_mfma_f32_32x32x16_bf16 v[96:111], v[132:135], v[116:119], v[96:111]
	s_waitcnt lgkmcnt(2)
	v_mfma_f32_32x32x16_bf16 v[80:95], v[128:131], v[120:123], v[80:95]
	v_mfma_f32_32x32x16_bf16 v[96:111], v[42:45], v[120:123], v[96:111]
	s_waitcnt lgkmcnt(0)
	v_mfma_f32_32x32x16_bf16 v[80:95], v[38:41], v[124:127], v[80:95]
	v_mfma_f32_32x32x16_bf16 v[96:111], v[34:37], v[124:127], v[96:111]
	s_setprio 0
	s_cmp_lg_u32 s61, 0
	s_cbranch_scc1 .Lmy_dma_mid_skip
	s_cmp_lt_i32 s32, 5
	s_cbranch_scc1 .Lmy_dma_mid_skip
	v_add_u32_e32 v214, -3, v192
	v_mul_lo_u32 v214, v214, s53
	v_mov_b32_e32 v215, 0
	s_sub_i32 s32, s63, s45
	s_add_i32 s32, s32, 0x8000
	v_lshl_add_u64 v[212:213], v[154:155], 0, v[214:215]
	v_lshl_add_u64 v[216:217], v[156:157], 0, v[214:215]
	v_lshl_add_u64 v[214:215], v[212:213], 0, s[86:87]
	s_add_i32 m0, s32, 0x10000
	s_nop 0
	global_load_lds_dwordx4 v[214:215], off
	s_add_i32 m0, s32, 0x14000
	v_lshl_add_u64 v[214:215], v[212:213], 0, s[88:89]
	global_load_lds_dwordx4 v[216:217], off
	s_add_i32 m0, s32, 0x11000
	s_nop 0
	global_load_lds_dwordx4 v[214:215], off
	v_lshl_add_u64 v[214:215], v[216:217], 0, s[90:91]
	s_add_i32 m0, s32, 0x15000
	s_nop 0
	global_load_lds_dwordx4 v[214:215], off
	v_lshl_add_u64 v[214:215], v[212:213], 0, s[92:93]
	s_add_i32 m0, s32, 0x12000
	v_lshl_add_u64 v[212:213], v[212:213], 0, s[96:97]
	global_load_lds_dwordx4 v[214:215], off
	v_lshl_add_u64 v[214:215], v[216:217], 0, s[94:95]
	s_add_i32 m0, s32, 0x16000
	s_nop 0
	global_load_lds_dwordx4 v[214:215], off
	s_add_i32 m0, s32, 0x13000
	s_nop 0
	global_load_lds_dwordx4 v[212:213], off
	v_lshl_add_u64 v[212:213], v[216:217], 0, s[72:73]
	s_add_i32 m0, s32, 0x17000
	s_nop 0
	global_load_lds_dwordx4 v[212:213], off

; DI unsigned cvtpk(float lo, float hi) { f32x2_t v = {lo, hi}; bf16x2_t b = __builtin_convertvector(v, bf16x2_t); return __builtin_bit_cast(unsigned, b); }
; #define MFMA32(a, b, c) __builtin_amdgcn_mfma_f32_32x32x16_bf16((a), (b), (c), 0, 0, 0)
; #define D3_VLD(buf, g) do { _Pragma("unroll") for (int dt = 0; dt < 4; ++dt) { const unsigned char* vp = tb + voff[dt] + (((g) >> 1) * 32 + 16 * ((g) & 1)) * 256; \
;                     vlo[buf][dt] = vtr(vp); vhi[buf][dt] = vtr(vp + 8 * 256); } } while (0)
; DI void diff_unit(unsigned char* smem, const bf16* __restrict__ QKV, bf16* __restrict__ Y, int h, int qb, float lam, float outscale, const float* __restrict__ gain, float kn0, float kn1, int tid) {
;     ...
;             float rs = 0.f;
; #pragma unroll
;             for (int kh = 0; kh < 2; ++kh)
; #pragma unroll
;                 for (int r = 0; r < 16; ++r) { const float e = __builtin_amdgcn_exp2f(p[kh][r] * c1 + t); p[kh][r] = e; rs += e; }
;             l_run += rs;
;             {
;                 s16x4 vlo[2][4], vhi[2][4];
;     ...
;                 D3_VLD(0, 0);
; #pragma unroll
;                 for (int g = 0; g < 4; ++g) {
;                     const int kh = g >> 1, s = g & 1;
;                     if (g < 3) D3_VLD((g + 1) & 1, g + 1);
;                     v4u w; w.x = cvtpk(p[kh][8 * s + 0], p[kh][8 * s + 1]); w.y = cvtpk(p[kh][8 * s + 2], p[kh][8 * s + 3]); w.z = cvtpk(p[kh][8 * s + 4], p[kh][8 * s + 5]); w.w = cvtpk(p[kh][8 * s + 6], p[kh][8 * s + 7]);
;                     const bf16x8 pf = __builtin_bit_cast(bf16x8, w);
;                     __builtin_amdgcn_sched_barrier(0);
; #pragma unroll
;                     for (int dt = 0; dt < 4; ++dt) {
;                         const bf16x8 vf = __builtin_shufflevector(vlo[g & 1][dt], vhi[g & 1][dt], 0, 1, 2, 3, 4, 5, 6, 7);
;                         o[dt] = MFMA32(vf, pf, o[dt]);
;                     }
;                     __builtin_amdgcn_sched_barrier(0);
;                 }
;     ...
;             }
;             if (mine_next) {
;                 const float dmin = (float)(qpos - (64 * (j - 2) + 63));
;                 dead = (__all((bq + slope2 * dmin) < (m_run - 150.0f)) != 0);
;             }
.LBB0_219:
	s_or_b64 exec, exec, s[16:17]
	v_add_u32_e32 v161, s81, v187
	s_nop 3
	v_fmamk_f32 v35, v80, 0x3e38aa3b, v34
	v_fmamk_f32 v36, v81, 0x3e38aa3b, v34
	v_fmamk_f32 v37, v82, 0x3e38aa3b, v34
	v_fmamk_f32 v38, v83, 0x3e38aa3b, v34
	v_fmamk_f32 v39, v84, 0x3e38aa3b, v34
	v_fmamk_f32 v40, v85, 0x3e38aa3b, v34
	v_fmamk_f32 v41, v86, 0x3e38aa3b, v34
	v_fmamk_f32 v42, v87, 0x3e38aa3b, v34
	v_fmamk_f32 v43, v88, 0x3e38aa3b, v34
	v_fmamk_f32 v44, v89, 0x3e38aa3b, v34
	v_fmamk_f32 v45, v90, 0x3e38aa3b, v34
	v_fmamk_f32 v80, v91, 0x3e38aa3b, v34
	v_fmamk_f32 v81, v92, 0x3e38aa3b, v34
	v_fmamk_f32 v82, v93, 0x3e38aa3b, v34
	v_fmamk_f32 v83, v94, 0x3e38aa3b, v34
	v_fmamk_f32 v84, v95, 0x3e38aa3b, v34
	v_fmamk_f32 v85, v96, 0x3e38aa3b, v34
	v_fmamk_f32 v86, v97, 0x3e38aa3b, v34
	v_fmamk_f32 v87, v98, 0x3e38aa3b, v34
	v_fmamk_f32 v88, v99, 0x3e38aa3b, v34
	v_fmamk_f32 v89, v100, 0x3e38aa3b, v34
	v_fmamk_f32 v90, v101, 0x3e38aa3b, v34
	v_fmamk_f32 v91, v102, 0x3e38aa3b, v34
	v_fmamk_f32 v92, v103, 0x3e38aa3b, v34
	v_fmamk_f32 v93, v104, 0x3e38aa3b, v34
	v_fmamk_f32 v94, v105, 0x3e38aa3b, v34
	v_fmamk_f32 v95, v106, 0x3e38aa3b, v34
	v_fmamk_f32 v96, v107, 0x3e38aa3b, v34
	v_fmamk_f32 v97, v108, 0x3e38aa3b, v34
	v_fmamk_f32 v98, v109, 0x3e38aa3b, v34
	v_fmamk_f32 v99, v110, 0x3e38aa3b, v34
	v_fmac_f32_e32 v34, 0x3e38aa3b, v111
	v_add_u32_e32 v163, s81, v32
	v_add_u32_e32 v170, s81, v188
	v_add_u32_e32 v172, s81, v189
	ds_read_b64_tr_b16 v[100:101], v161
	ds_read_b64_tr_b16 v[102:103], v161 offset:2048
	ds_read_b64_tr_b16 v[104:105], v161 offset:4096
	ds_read_b64_tr_b16 v[106:107], v161 offset:6144
	ds_read_b64_tr_b16 v[108:109], v163 offset:16384
	ds_read_b64_tr_b16 v[110:111], v163 offset:18432
	ds_read_b64_tr_b16 v[128:129], v163 offset:20480
	ds_read_b64_tr_b16 v[130:131], v163 offset:22528
	ds_read_b64_tr_b16 v[132:133], v170 offset:16384
	ds_read_b64_tr_b16 v[134:135], v170 offset:18432
	ds_read_b64_tr_b16 v[136:137], v170 offset:20480
	ds_read_b64_tr_b16 v[138:139], v170 offset:22528
	ds_read_b64_tr_b16 v[140:141], v172 offset:16384
	ds_read_b64_tr_b16 v[142:143], v172 offset:18432
	ds_read_b64_tr_b16 v[144:145], v172 offset:20480
	ds_read_b64_tr_b16 v[146:147], v172 offset:22528
	v_exp_f32_e32 v35, v35
	v_exp_f32_e32 v36, v36
	v_exp_f32_e32 v37, v37
	v_exp_f32_e32 v38, v38
	v_exp_f32_e32 v39, v39
	v_exp_f32_e32 v40, v40
	v_exp_f32_e32 v41, v41
	v_exp_f32_e32 v42, v42
	v_exp_f32_e32 v43, v43
	v_exp_f32_e32 v44, v44
	v_exp_f32_e32 v45, v45
	v_exp_f32_e32 v80, v80
	v_exp_f32_e32 v81, v81
	v_exp_f32_e32 v82, v82
	v_exp_f32_e32 v83, v83
	v_exp_f32_e32 v84, v84
	v_exp_f32_e32 v85, v85
	v_exp_f32_e32 v86, v86
	v_exp_f32_e32 v87, v87
	v_exp_f32_e32 v88, v88
	v_exp_f32_e32 v89, v89
	v_exp_f32_e32 v90, v90
	v_exp_f32_e32 v91, v91
	v_exp_f32_e32 v92, v92
	v_exp_f32_e32 v93, v93
	v_exp_f32_e32 v94, v94
	v_exp_f32_e32 v95, v95
	v_exp_f32_e32 v96, v96
	v_exp_f32_e32 v97, v97
	v_exp_f32_e32 v98, v98
	v_exp_f32_e32 v99, v99
	v_exp_f32_e32 v34, v34
	v_cvt_pk_bf16_f32 v194, v35, v36
	v_cvt_pk_bf16_f32 v195, v37, v38
	v_cvt_pk_bf16_f32 v196, v39, v40
	v_cvt_pk_bf16_f32 v197, v41, v42
	s_waitcnt lgkmcnt(0)
	s_nop 0
	s_setprio 1
	v_mfma_f32_32x32x16_bf16 v[64:79], v[100:103], v[194:197], v[64:79]
	v_mfma_f32_32x32x16_bf16 v[48:63], v[108:111], v[194:197], v[48:63]
	v_mfma_f32_32x32x16_bf16 v[16:31], v[132:135], v[194:197], v[16:31]
	v_mfma_f32_32x32x16_bf16 v[0:15], v[140:143], v[194:197], v[0:15]
	ds_read_b64_tr_b16 v[100:101], v161 offset:8192
	ds_read_b64_tr_b16 v[102:103], v161 offset:10240
	ds_read_b64_tr_b16 v[108:109], v163 offset:24576
	ds_read_b64_tr_b16 v[110:111], v163 offset:26624
	ds_read_b64_tr_b16 v[132:133], v170 offset:24576
	ds_read_b64_tr_b16 v[134:135], v170 offset:26624
	ds_read_b64_tr_b16 v[140:141], v172 offset:24576
	ds_read_b64_tr_b16 v[142:143], v172 offset:26624
	v_cvt_pk_bf16_f32 v194, v43, v44
	v_cvt_pk_bf16_f32 v195, v45, v80
	v_cvt_pk_bf16_f32 v196, v81, v82
	v_cvt_pk_bf16_f32 v197, v83, v84
	s_nop 1
	v_mfma_f32_32x32x16_bf16 v[64:79], v[104:107], v[194:197], v[64:79]
	v_mfma_f32_32x32x16_bf16 v[48:63], v[128:131], v[194:197], v[48:63]
	v_mfma_f32_32x32x16_bf16 v[16:31], v[136:139], v[194:197], v[16:31]
	v_mfma_f32_32x32x16_bf16 v[0:15], v[144:147], v[194:197], v[0:15]
	ds_read_b64_tr_b16 v[104:105], v161 offset:12288
	ds_read_b64_tr_b16 v[106:107], v161 offset:14336
	ds_read_b64_tr_b16 v[128:129], v163 offset:28672
	ds_read_b64_tr_b16 v[130:131], v163 offset:30720
	ds_read_b64_tr_b16 v[136:137], v170 offset:28672
	ds_read_b64_tr_b16 v[138:139], v170 offset:30720
	ds_read_b64_tr_b16 v[144:145], v172 offset:28672
	ds_read_b64_tr_b16 v[146:147], v172 offset:30720
	v_cvt_pk_bf16_f32 v194, v85, v86
	v_cvt_pk_bf16_f32 v195, v87, v88
	v_cvt_pk_bf16_f32 v196, v89, v90
	v_cvt_pk_bf16_f32 v197, v91, v92
	s_waitcnt lgkmcnt(0)
	s_nop 0
	v_mfma_f32_32x32x16_bf16 v[64:79], v[100:103], v[194:197], v[64:79]
	v_mfma_f32_32x32x16_bf16 v[48:63], v[108:111], v[194:197], v[48:63]
	v_mfma_f32_32x32x16_bf16 v[16:31], v[132:135], v[194:197], v[16:31]
	v_mfma_f32_32x32x16_bf16 v[0:15], v[140:143], v[194:197], v[0:15]
	v_cvt_pk_bf16_f32 v100, v93, v94
	v_cvt_pk_bf16_f32 v101, v95, v96
	v_cvt_pk_bf16_f32 v102, v97, v98
	v_cvt_pk_bf16_f32 v103, v99, v34
	s_nop 1
	v_mfma_f32_32x32x16_bf16 v[64:79], v[104:107], v[100:103], v[64:79]
	v_mfma_f32_32x32x16_bf16 v[48:63], v[128:131], v[100:103], v[48:63]
	v_mfma_f32_32x32x16_bf16 v[16:31], v[136:139], v[100:103], v[16:31]
	v_mfma_f32_32x32x16_bf16 v[0:15], v[144:147], v[100:103], v[0:15]
	s_setprio 0
	s_mov_b64 s[16:17], 0
	s_and_saveexec_b64 s[56:57], s[14:15]
	s_cbranch_execz .LBB0_221
	v_cvt_f32_i32_e32 v100, v190
	v_mul_f32_e32 v172, v160, v100
	v_pk_add_f32 v[100:101], v[158:159], v[172:173]
	s_nop 0
	v_cmp_lt_f32_e32 vcc, v100, v101
	s_cmp_eq_u64 vcc, exec
	s_cselect_b64 s[14:15], -1, 0
	s_and_b64 s[16:17], s[14:15], exec
